# latent attention: softmax exponent via one fma per score (was sub+mul), QK^T and second PV fragment reads batched ahead of their MFMAs
# speedup vs baseline: 1.0374x; 1.0057x over previous
.LBB0_581:
	s_mov_b32 s0, 0xf149f2ca
	s_nop 6
	v_max3_f32 v0, v64, s0, v65
	v_max3_f32 v0, v0, v66, v67
	v_max3_f32 v0, v0, v68, v69
	v_max3_f32 v0, v0, v70, v71
	v_max3_f32 v0, v0, v72, v73
	v_max3_f32 v0, v0, v74, v75
	v_max3_f32 v0, v0, v76, v77
	v_max3_f32 v0, v0, v78, v79
	v_max3_f32 v0, v0, v48, v49
	v_max3_f32 v0, v0, v50, v51
	v_max3_f32 v0, v0, v52, v53
	v_max3_f32 v0, v0, v54, v55
	v_and_b32_e32 v3, 64, v213
	v_max3_f32 v0, v0, v56, v57
	v_xor_b32_e32 v2, 32, v213
	v_add_u32_e32 v3, 64, v3
	v_max3_f32 v0, v0, v58, v59
	v_cmp_lt_i32_e32 vcc, v2, v3
	v_max3_f32 v0, v0, v60, v61
	v_max3_f32 v0, v0, v62, v63
	v_cndmask_b32_e32 v2, v213, v2, vcc
	v_lshlrev_b32_e32 v2, 2, v2
	ds_bpermute_b32 v2, v2, v0
	s_waitcnt lgkmcnt(0)
	v_max3_f32 v14, v151, v0, v2
	s_mov_b32 s79, 0x3fb8aa3b
	v_mul_f32_e32 v192, 0xbfb8aa3b, v14
	v_fma_f32 v6, v68, s79, v192
	v_exp_f32_e32 v15, v6
	v_fma_f32 v6, v69, s79, v192
	v_fma_f32 v2, v64, s79, v192
	v_exp_f32_e32 v64, v6
	v_fma_f32 v6, v70, s79, v192
	v_fma_f32 v3, v65, s79, v192
	v_exp_f32_e32 v65, v6
	v_fma_f32 v6, v71, s79, v192
	v_fma_f32 v4, v66, s79, v192
	v_exp_f32_e32 v66, v6
	v_fma_f32 v6, v72, s79, v192
	v_exp_f32_e32 v2, v2
	v_exp_f32_e32 v3, v3
	v_fma_f32 v5, v67, s79, v192
	v_exp_f32_e32 v67, v6
	v_fma_f32 v6, v73, s79, v192
	v_exp_f32_e32 v4, v4
	v_exp_f32_e32 v5, v5
	v_exp_f32_e32 v68, v6
	v_fma_f32 v6, v74, s79, v192
	v_cvt_pk_bf16_f32 v10, v2, v3
	v_add_f32_e32 v2, 0, v2
	v_exp_f32_e32 v69, v6
	v_fma_f32 v6, v75, s79, v192
	v_add_f32_e32 v2, v3, v2
	v_add_f32_e32 v2, v4, v2
	v_exp_f32_e32 v70, v6
	v_fma_f32 v6, v76, s79, v192
	v_add_f32_e32 v2, v5, v2
	v_add_f32_e32 v2, v15, v2
	v_exp_f32_e32 v71, v6
	v_fma_f32 v6, v77, s79, v192
	v_add_f32_e32 v2, v64, v2
	v_add_f32_e32 v2, v65, v2
	v_exp_f32_e32 v72, v6
	v_fma_f32 v6, v78, s79, v192
	v_add_f32_e32 v2, v66, v2
	v_add_f32_e32 v2, v67, v2
	v_exp_f32_e32 v73, v6
	v_fma_f32 v6, v79, s79, v192
	v_add_f32_e32 v2, v68, v2
	v_add_f32_e32 v2, v69, v2
	v_exp_f32_e32 v74, v6
	v_add_f32_e32 v2, v70, v2
	v_add_f32_e32 v2, v71, v2
	v_add_f32_e32 v2, v72, v2
	v_add_f32_e32 v2, v73, v2
	v_cvt_pk_bf16_f32 v12, v15, v64
	v_add_f32_e32 v64, v74, v2
	v_fma_f32 v2, v48, s79, v192
	v_cvt_pk_bf16_f32 v13, v65, v66
	v_exp_f32_e32 v65, v2
	v_fma_f32 v2, v49, s79, v192
	v_exp_f32_e32 v66, v2
	v_fma_f32 v2, v50, s79, v192
	v_cvt_pk_bf16_f32 v6, v67, v68
	v_exp_f32_e32 v67, v2
	v_fma_f32 v2, v51, s79, v192
	v_exp_f32_e32 v68, v2
	v_fma_f32 v2, v52, s79, v192
	v_exp_f32_e32 v52, v2
	v_fma_f32 v2, v53, s79, v192
	v_exp_f32_e32 v53, v2
	v_fma_f32 v2, v54, s79, v192
	v_exp_f32_e32 v54, v2
	v_fma_f32 v2, v55, s79, v192
	v_exp_f32_e32 v55, v2
	v_fma_f32 v2, v56, s79, v192
	v_exp_f32_e32 v56, v2
	v_fma_f32 v2, v57, s79, v192
	v_exp_f32_e32 v57, v2
	v_fma_f32 v2, v58, s79, v192
	v_exp_f32_e32 v58, v2
	v_fma_f32 v2, v59, s79, v192
	v_exp_f32_e32 v59, v2
	v_fma_f32 v2, v60, s79, v192
	v_exp_f32_e32 v60, v2
	v_fma_f32 v2, v61, s79, v192
	v_exp_f32_e32 v61, v2
	v_fma_f32 v2, v62, s79, v192
	v_exp_f32_e32 v62, v2
	v_fma_f32 v2, v63, s79, v192
	v_add_f32_e32 v63, v65, v64
	v_add_f32_e32 v63, v66, v63
	v_add_f32_e32 v63, v67, v63
	v_add_f32_e32 v63, v68, v63
	v_cvt_pk_bf16_f32 v50, v52, v53
	v_add_f32_e32 v52, v52, v63
	v_add_f32_e32 v52, v53, v52
	v_add_f32_e32 v52, v54, v52
	v_add_f32_e32 v52, v55, v52
	v_add_f32_e32 v52, v56, v52
	v_add_f32_e32 v52, v57, v52
	v_fma_f32 v0, v151, s79, v192
	v_add_f32_e32 v52, v58, v52
	v_add_f32_e32 v52, v59, v52
	v_add_f32_e32 v52, v60, v52
	v_exp_f32_e32 v0, v0
	v_add_u32_e32 v53, 0x2000, v150
	v_cvt_pk_bf16_f32 v11, v4, v5
	v_exp_f32_e32 v15, v2
	v_cvt_pk_bf16_f32 v51, v54, v55
	v_cvt_pk_bf16_f32 v2, v56, v57
	v_cvt_pk_bf16_f32 v3, v58, v59
	v_cvt_pk_bf16_f32 v4, v60, v61
	v_add_f32_e32 v52, v61, v52
	ds_read2_b64 v[54:57], v53 offset1:2
	ds_read2_b64 v[58:61], v53 offset0:4 offset1:6
	v_pk_mul_f32 v[46:47], v[46:47], v[0:1] op_sel_hi:[1,0]
	v_pk_mul_f32 v[44:45], v[44:45], v[0:1] op_sel_hi:[1,0]
	v_pk_mul_f32 v[42:43], v[42:43], v[0:1] op_sel_hi:[1,0]
	v_pk_mul_f32 v[40:41], v[40:41], v[0:1] op_sel_hi:[1,0]
	v_pk_mul_f32 v[38:39], v[38:39], v[0:1] op_sel_hi:[1,0]
	v_pk_mul_f32 v[36:37], v[36:37], v[0:1] op_sel_hi:[1,0]
	v_pk_mul_f32 v[34:35], v[34:35], v[0:1] op_sel_hi:[1,0]
	v_pk_mul_f32 v[32:33], v[32:33], v[0:1] op_sel_hi:[1,0]
	v_cvt_pk_bf16_f32 v7, v69, v70
	v_cvt_pk_bf16_f32 v8, v71, v72
	s_waitcnt lgkmcnt(1)
	v_mfma_f32_32x32x16_bf16 v[32:47], v[54:57], v[10:13], v[32:47]
	v_cvt_pk_bf16_f32 v9, v73, v74
	ds_read2_b64 v[54:57], v53 offset0:8 offset1:10
	v_cvt_pk_bf16_f32 v48, v65, v66
	v_cvt_pk_bf16_f32 v49, v67, v68
	v_cvt_pk_bf16_f32 v5, v62, v15
	v_pk_mul_f32 v[30:31], v[30:31], v[0:1] op_sel_hi:[1,0]
	v_pk_mul_f32 v[28:29], v[28:29], v[0:1] op_sel_hi:[1,0]
	s_waitcnt lgkmcnt(1)
	v_mfma_f32_32x32x16_bf16 v[32:47], v[58:61], v[6:9], v[32:47]
	v_mul_f32_e64 v26, v26, v0
	v_mul_f32_e64 v27, v27, v0
	v_mul_f32_e64 v24, v24, v0
	v_mul_f32_e64 v25, v25, v0
	v_mul_f32_e64 v22, v22, v0
	v_mul_f32_e64 v23, v23, v0
	v_pk_mul_f32 v[20:21], v[20:21], v[0:1] op_sel_hi:[1,0]
	v_pk_mul_f32 v[18:19], v[18:19], v[0:1] op_sel_hi:[1,0]
	v_pk_mul_f32 v[16:17], v[16:17], v[0:1] op_sel_hi:[1,0]
	v_add_f32_e32 v52, v62, v52
	s_waitcnt lgkmcnt(0)
	v_mfma_f32_32x32x16_bf16 v[32:47], v[54:57], v[48:51], v[32:47]
	ds_read2_b64 v[54:57], v53 offset0:12 offset1:14
	v_add_u32_e32 v53, 0x3000, v150
	v_mov_b32_e32 v151, v14
	ds_read2_b64 v[58:61], v53 offset0:32 offset1:34
	ds_read2_b64 v[62:65], v53 offset0:36 offset1:38
	ds_read2_b64 v[66:69], v53 offset0:40 offset1:42
	ds_read2_b64 v[70:73], v53 offset0:44 offset1:46
	s_waitcnt lgkmcnt(4)
	v_mfma_f32_32x32x16_bf16 v[32:47], v[54:57], v[2:5], v[32:47]
	s_waitcnt lgkmcnt(3)
	v_mfma_f32_32x32x16_bf16 v[16:31], v[58:61], v[10:13], v[16:31]
	s_waitcnt lgkmcnt(2)
	v_mfma_f32_32x32x16_bf16 v[16:31], v[62:65], v[6:9], v[16:31]
	s_waitcnt lgkmcnt(1)
	v_mfma_f32_32x32x16_bf16 v[16:31], v[66:69], v[48:51], v[16:31]
	s_waitcnt lgkmcnt(0)
	v_mfma_f32_32x32x16_bf16 v[16:31], v[70:73], v[2:5], v[16:31]
	v_add_f32_e32 v2, v15, v52
	v_fmac_f32_e32 v2, v105, v0
	v_mov_b32_e32 v105, v2
	s_cmp_lg_u32 s78, 0
	s_cbranch_scc1 .LBB0_576
	s_branch .Lat_cons

.Lat_go:
	ds_write_b16 v145, v0 offset:8192
	ds_write_b16 v145, v2 offset:8328
	ds_write_b16 v145, v3 offset:8464
	ds_write_b16 v145, v4 offset:8600
	ds_write_b16 v145, v5 offset:8736
	ds_write_b16 v145, v6 offset:8872
	ds_write_b16 v145, v7 offset:9008
	ds_write_b16 v145, v8 offset:9144
	s_and_b64 vcc, exec, s[66:67]
	s_waitcnt lgkmcnt(0)
	s_barrier
	ds_read_b128 v[2:5], v146
	ds_read_b128 v[6:9], v146 offset:4096
	ds_read_b128 v[10:13], v147
	ds_read_b128 v[152:155], v147 offset:4096
	ds_read_b128 v[156:159], v148
	s_waitcnt lgkmcnt(4)
	v_mfma_f32_32x32x16_bf16 v[64:79], v[2:5], v[80:83], 0
	ds_read_b128 v[2:5], v148 offset:4096
	s_waitcnt lgkmcnt(4)
	v_mfma_f32_32x32x16_bf16 v[48:63], v[6:9], v[80:83], 0
	ds_read_b128 v[6:9], v149
	s_waitcnt lgkmcnt(4)
	v_mfma_f32_32x32x16_bf16 v[64:79], v[10:13], v[84:87], v[64:79]
	ds_read_b128 v[10:13], v149 offset:4096
	s_waitcnt lgkmcnt(4)
	v_mfma_f32_32x32x16_bf16 v[48:63], v[152:155], v[84:87], v[48:63]
	s_waitcnt lgkmcnt(3)
	v_mfma_f32_32x32x16_bf16 v[64:79], v[156:159], v[88:91], v[64:79]
	s_waitcnt lgkmcnt(2)
	v_mfma_f32_32x32x16_bf16 v[48:63], v[2:5], v[88:91], v[48:63]
	s_waitcnt lgkmcnt(1)
	v_mfma_f32_32x32x16_bf16 v[64:79], v[6:9], v[92:95], v[64:79]
	s_waitcnt lgkmcnt(0)
	v_mfma_f32_32x32x16_bf16 v[48:63], v[10:13], v[92:95], v[48:63]
	s_cbranch_vccnz .LBB0_581
	v_add_u32_e32 v0, s32, v101
	v_sub_u32_e32 v2, v108, v0
	v_cmp_lt_u32_e32 vcc, s72, v2
	v_sub_u32_e32 v2, v0, v108
	s_movk_i32 s0, 0x101
	s_nop 2
	v_cndmask_b32_e32 v64, v216, v64, vcc
	v_cmp_gt_u32_e32 vcc, s0, v2
	v_sub_u32_e32 v2, v110, v0
	s_nop 0
	v_cndmask_b32_e32 v65, v216, v65, vcc
	v_cmp_lt_u32_e32 vcc, s72, v2
	v_sub_u32_e32 v2, v111, v0
	s_nop 0
	v_cndmask_b32_e32 v66, v216, v66, vcc
	v_cmp_lt_u32_e32 vcc, s72, v2
	v_sub_u32_e32 v2, v112, v0
	s_nop 0
	v_cndmask_b32_e32 v67, v216, v67, vcc
	v_cmp_lt_u32_e32 vcc, s72, v2
	v_sub_u32_e32 v2, v113, v0
	s_nop 0
	v_cndmask_b32_e32 v68, v216, v68, vcc
	v_cmp_lt_u32_e32 vcc, s72, v2
	v_sub_u32_e32 v2, v114, v0
	s_nop 0
	v_cndmask_b32_e32 v69, v216, v69, vcc
	v_cmp_lt_u32_e32 vcc, s72, v2
	v_sub_u32_e32 v2, v115, v0
	s_nop 0
	v_cndmask_b32_e32 v70, v216, v70, vcc
	v_cmp_lt_u32_e32 vcc, s72, v2
	v_sub_u32_e32 v2, v116, v0
	s_nop 0
	v_cndmask_b32_e32 v71, v216, v71, vcc
	v_cmp_lt_u32_e32 vcc, s72, v2
	v_sub_u32_e32 v2, v117, v0
	s_nop 0
	v_cndmask_b32_e32 v72, v216, v72, vcc
	v_cmp_lt_u32_e32 vcc, s72, v2
	v_sub_u32_e32 v2, v118, v0
	s_nop 0
	v_cndmask_b32_e32 v73, v216, v73, vcc
	v_cmp_lt_u32_e32 vcc, s72, v2
	v_sub_u32_e32 v2, v119, v0
	s_nop 0
	v_cndmask_b32_e32 v74, v216, v74, vcc
	v_cmp_lt_u32_e32 vcc, s72, v2
	v_sub_u32_e32 v2, v120, v0
	s_nop 0
	v_cndmask_b32_e32 v75, v216, v75, vcc
	v_cmp_lt_u32_e32 vcc, s72, v2
	v_sub_u32_e32 v2, v121, v0
	s_nop 0
	v_cndmask_b32_e32 v76, v216, v76, vcc
	v_cmp_lt_u32_e32 vcc, s72, v2
	v_sub_u32_e32 v2, v122, v0
	s_nop 0
	v_cndmask_b32_e32 v77, v216, v77, vcc
	v_cmp_lt_u32_e32 vcc, s72, v2
	v_sub_u32_e32 v2, v123, v0
	s_nop 0
	v_cndmask_b32_e32 v78, v216, v78, vcc
	v_cmp_lt_u32_e32 vcc, s72, v2
	v_sub_u32_e32 v2, v124, v0
	s_nop 0
	v_cndmask_b32_e32 v79, v216, v79, vcc
	v_cmp_lt_u32_e32 vcc, s72, v2
	v_sub_u32_e32 v2, v125, v0
	s_nop 0
	v_cndmask_b32_e32 v48, v216, v48, vcc
	v_cmp_lt_u32_e32 vcc, s72, v2
	v_sub_u32_e32 v2, v126, v0
	s_nop 0
	v_cndmask_b32_e32 v49, v216, v49, vcc
	v_cmp_lt_u32_e32 vcc, s72, v2
	v_sub_u32_e32 v2, v127, v0
	s_nop 0
	v_cndmask_b32_e32 v50, v216, v50, vcc
	v_cmp_lt_u32_e32 vcc, s72, v2
	v_sub_u32_e32 v2, v128, v0
	s_nop 0
	v_cndmask_b32_e32 v51, v216, v51, vcc
	v_cmp_lt_u32_e32 vcc, s72, v2
	v_sub_u32_e32 v2, v129, v0
	s_nop 0
	v_cndmask_b32_e32 v52, v216, v52, vcc
	v_cmp_lt_u32_e32 vcc, s72, v2
	v_sub_u32_e32 v2, v130, v0
	s_nop 0
	v_cndmask_b32_e32 v53, v216, v53, vcc
	v_cmp_lt_u32_e32 vcc, s72, v2
	v_sub_u32_e32 v2, v131, v0
	s_nop 0
	v_cndmask_b32_e32 v54, v216, v54, vcc
	v_cmp_lt_u32_e32 vcc, s72, v2
	v_sub_u32_e32 v2, v132, v0
	s_nop 0
	v_cndmask_b32_e32 v55, v216, v55, vcc
	v_cmp_lt_u32_e32 vcc, s72, v2
	v_sub_u32_e32 v2, v133, v0
	s_nop 0
	v_cndmask_b32_e32 v56, v216, v56, vcc
	v_cmp_lt_u32_e32 vcc, s72, v2
	v_sub_u32_e32 v2, v138, v0
	s_nop 0
	v_cndmask_b32_e32 v57, v216, v57, vcc
	v_cmp_lt_u32_e32 vcc, s72, v2
	v_sub_u32_e32 v2, v139, v0
	s_nop 0
	v_cndmask_b32_e32 v58, v216, v58, vcc
	v_cmp_lt_u32_e32 vcc, s72, v2
	v_sub_u32_e32 v2, v140, v0
	s_nop 0
	v_cndmask_b32_e32 v59, v216, v59, vcc
	v_cmp_lt_u32_e32 vcc, s72, v2
	v_sub_u32_e32 v2, v141, v0
	s_nop 0
	v_cndmask_b32_e32 v60, v216, v60, vcc
	v_cmp_lt_u32_e32 vcc, s72, v2
	v_sub_u32_e32 v2, v142, v0
	v_sub_u32_e32 v0, v143, v0
	v_cndmask_b32_e32 v61, v216, v61, vcc
	v_cmp_lt_u32_e32 vcc, s72, v2
	s_nop 1
	v_cndmask_b32_e32 v62, v216, v62, vcc
	v_cmp_lt_u32_e32 vcc, s72, v0
	s_nop 1
	v_cndmask_b32_e32 v63, v216, v63, vcc
	s_branch .LBB0_581
